# GEMM accumulator zero-init with 64 v_mov_b64 instead of 128 v_mov_b32 per tile (all six GEMM instances), on top of the LRU parameter-load hoist
# baseline (speedup 1.0000x reference)
; template <class Epi, class Sched>
; __device__ __forceinline__ void gemm_phase(LAS unsigned char* lds, const int K, const Sched& S, const Epi& E) {
;     ...
;         const char* nA = has_next ? nxt.a : cA; const char* nB = has_next ? nxt.b : cB;
;         const int nt = cur.pad;
; #pragma unroll 1
;         for (int t = 0; t < nt; t += 2) {
;             const bool last = (t == nt - 2);
;             const char* a1 = cA + (size_t)(t + 1) * kstep;
;             const char* a2 = last ? nA : cA + (size_t)(t + 2) * kstep; const char* b2 = last ? nB : cB + (size_t)(t + 2) * kstep;
;             const char* a3 = a2 + kstep; const char* b3 = b2 + kstep;
;     ...
;         for (int a = 0; a < 2; ++a)
; #pragma unroll
;             for (int b = 0; b < 2; ++b)
; #pragma unroll
;                 for (int m = 0; m < 4; ++m)
; #pragma unroll
;                     for (int n = 0; n < 2; ++n) acc[a][b][m][n] = (f32x4){0.f, 0.f, 0.f, 0.f};
.LBB0_402:
	s_and_b64 s[4:5], s[52:53], exec
	s_cselect_b32 s2, s49, s9
	s_cselect_b32 s4, s48, s8
	s_cselect_b32 s5, s51, s39
	s_cselect_b32 s10, s50, s38
	s_add_u32 s8, s8, 0x40080
	s_addc_u32 s9, s9, 0
	s_add_u32 s11, s38, 0x100
	s_addc_u32 s12, s39, 0
	s_mov_b32 s13, -2
	v_mov_b64_e32 v[0:1], 0
	v_mov_b64_e32 v[2:3], 0
	v_mov_b64_e32 v[4:5], 0
	v_mov_b64_e32 v[6:7], 0
	v_mov_b64_e32 v[16:17], 0
	v_mov_b64_e32 v[18:19], 0
	v_mov_b64_e32 v[20:21], 0
	v_mov_b64_e32 v[22:23], 0
	v_mov_b64_e32 v[32:33], 0
	v_mov_b64_e32 v[34:35], 0
	v_mov_b64_e32 v[36:37], 0
	v_mov_b64_e32 v[38:39], 0
	v_mov_b64_e32 v[48:49], 0
	v_mov_b64_e32 v[50:51], 0
	v_mov_b64_e32 v[52:53], 0
	v_mov_b64_e32 v[54:55], 0
	v_mov_b64_e32 v[8:9], 0
	v_mov_b64_e32 v[10:11], 0
	v_mov_b64_e32 v[12:13], 0
	v_mov_b64_e32 v[14:15], 0
	v_mov_b64_e32 v[24:25], 0
	v_mov_b64_e32 v[26:27], 0
	v_mov_b64_e32 v[28:29], 0
	v_mov_b64_e32 v[30:31], 0
	v_mov_b64_e32 v[40:41], 0
	v_mov_b64_e32 v[42:43], 0
	v_mov_b64_e32 v[44:45], 0
	v_mov_b64_e32 v[46:47], 0
	v_mov_b64_e32 v[56:57], 0
	v_mov_b64_e32 v[58:59], 0
	v_mov_b64_e32 v[60:61], 0
	v_mov_b64_e32 v[62:63], 0
	v_mov_b64_e32 v[64:65], 0
	v_mov_b64_e32 v[66:67], 0
	v_mov_b64_e32 v[68:69], 0
	v_mov_b64_e32 v[70:71], 0
	v_mov_b64_e32 v[80:81], 0
	v_mov_b64_e32 v[82:83], 0
	v_mov_b64_e32 v[84:85], 0
	v_mov_b64_e32 v[86:87], 0
	v_mov_b64_e32 v[96:97], 0
	v_mov_b64_e32 v[98:99], 0
	v_mov_b64_e32 v[100:101], 0
	v_mov_b64_e32 v[102:103], 0
	v_mov_b64_e32 v[112:113], 0
	v_mov_b64_e32 v[114:115], 0
	v_mov_b64_e32 v[116:117], 0
	v_mov_b64_e32 v[118:119], 0
	v_mov_b64_e32 v[72:73], 0
	v_mov_b64_e32 v[74:75], 0
	v_mov_b64_e32 v[76:77], 0
	v_mov_b64_e32 v[78:79], 0
	v_mov_b64_e32 v[88:89], 0
	v_mov_b64_e32 v[90:91], 0
	v_mov_b64_e32 v[92:93], 0
	v_mov_b64_e32 v[94:95], 0
	v_mov_b64_e32 v[104:105], 0
	v_mov_b64_e32 v[106:107], 0
	v_mov_b64_e32 v[108:109], 0
	v_mov_b64_e32 v[110:111], 0
	v_mov_b64_e32 v[120:121], 0
	v_mov_b64_e32 v[122:123], 0
	v_mov_b64_e32 v[124:125], 0
	v_mov_b64_e32 v[126:127], 0

; #define PG8_STAGE(bufoff, gbase, voff) do { _Pragma("unroll") for (int _i = 0; _i < 2; ++_i) \
;         __builtin_amdgcn_global_load_lds((const unsigned*)((const char*)(gbase) + (voff)[_i]), (LAS unsigned*)(lds + (bufoff) + ldsw + _i * 8192), 16, 0, 0); } while (0)
; #define PG8_WAIT_V(n) asm volatile("s_waitcnt vmcnt(" #n ")" ::: "memory")
; #define PG8_BAR __builtin_amdgcn_s_barrier()
; template <class Epi, class Sched>
; __device__ __forceinline__ void gemm_phase(LAS unsigned char* lds, const int K, const Sched& S, const Epi& E) {
;     ...
;                 for (int n = 0; n < 2; ++n) acc[a][b][m][n] = (f32x4){0.f, 0.f, 0.f, 0.f};
;     bf16x8 At[4][2], B0[2][2], B1[2][2];
;     const char* cA = cur.a; const char* cB = cur.b;
;     PG8_STAGE(PG8_SB(0, 0), cB, voffB); PG8_STAGE(PG8_SB(0, 1), cB + hstep, voffB); PG8_STAGE(PG8_SA(0, 0), cA, voffA); PG8_STAGE(PG8_SA(0, 1), cA + hstep, voffA);
;     if (wr == 1) PG8_BAR;
;     PG8_WAIT_V(2); PG8_BAR;
;     PG8_STAGE(PG8_SB(1, 0), cB + kstep, voffB); PG8_STAGE(PG8_SA(1, 0), cA + kstep, voffA); PG8_STAGE(PG8_SB(1, 1), cB + hstep + kstep, voffB);
;     PG8_WAIT_V(6); PG8_BAR;
.LBB0_510:
	v_lshrrev_b32_e32 v16, 1, v3
	v_lshl_add_u64 v[8:9], s[34:35], 0, v[128:129]
	v_mov_b32_e32 v139, v129
	v_and_b32_e32 v16, 24, v16
	s_lshl_b32 s8, s8, 5
	v_lshl_add_u64 v[10:11], s[34:35], 0, v[138:139]
	v_mov_b32_e32 v143, v129
	v_and_b32_e32 v7, 15, v3
	v_lshlrev_b32_e32 v144, 1, v16
	v_lshlrev_b32_e32 v3, 2, v3
	s_and_b32 s10, s8, 0x60
	s_add_i32 m0, s2, 0x18000
	v_lshl_add_u64 v[8:9], v[8:9], 0, s[36:37]
	v_lshl_add_u64 v[12:13], s[28:29], 0, v[142:143]
	v_mov_b32_e32 v141, v129
	v_lshl_or_b32 v150, s9, 6, v7
	v_lshl_or_b32 v7, v7, 6, v144
	s_lshl_b32 s9, s9, 13
	v_and_b32_e32 v3, 32, v3
	s_lshl_b32 s8, s10, 7
	s_waitcnt vmcnt(2)
	s_barrier
	global_load_lds_dwordx4 v[8:9], off
	v_lshl_add_u64 v[8:9], v[10:11], 0, s[36:37]
	s_add_i32 m0, s2, 0x1a000
	s_add_i32 s11, s2, 0x8000
	v_lshl_add_u64 v[14:15], s[28:29], 0, v[140:141]
	v_bitop3_b32 v16, v7, s9, v3 bitop3:0xde
	v_bitop3_b32 v145, v7, s8, v3 bitop3:0xde
	global_load_lds_dwordx4 v[8:9], off
	v_lshl_add_u64 v[8:9], v[12:13], 0, s[36:37]
	s_mov_b32 m0, s11
	s_add_i32 s12, s2, 0xa000
	v_readlane_b32 s8, v252, 3
	global_load_lds_dwordx4 v[8:9], off
	v_lshl_add_u64 v[8:9], v[14:15], 0, s[36:37]
	s_mov_b32 m0, s12
	v_readlane_b32 s9, v252, 4
	global_load_lds_dwordx4 v[8:9], off
	s_add_i32 m0, s2, 0x1c000
	v_lshl_add_u64 v[8:9], s[8:9], 0, v[128:129]
	global_load_lds_dwordx4 v[8:9], off
	v_lshl_add_u64 v[8:9], s[8:9], 0, v[138:139]
	s_add_i32 m0, s2, 0x1e000
	v_lshlrev_b32_e32 v3, 16, v5
	global_load_lds_dwordx4 v[8:9], off
	v_and_b32_e32 v3, 0xfffe0000, v3
	v_lshl_add_u32 v3, v4, 13, v3
	v_and_b32_e32 v4, 1, v5
	v_lshl_or_b32 v3, v4, 6, v3
	v_lshl_add_u32 v4, v6, 1, v3
	v_lshlrev_b32_e32 v3, 16, v0
	v_and_b32_e32 v3, 0xfffe0000, v3
	v_lshl_add_u32 v1, v1, 13, v3
	v_and_b32_e32 v0, 1, v0
	v_readlane_b32 s8, v253, 36
	v_lshl_or_b32 v0, v0, 6, v1
	s_waitcnt vmcnt(6)
	v_readlane_b32 s9, v253, 37
	v_lshl_add_u32 v0, v2, 1, v0
	v_mov_b32_e32 v1, v129
	v_mov_b32_e32 v5, v129
	v_lshl_add_u64 v[148:149], s[8:9], 0, v[0:1]
	v_lshl_add_u64 v[146:147], s[8:9], 0, v[4:5]
	s_mov_b32 s13, -2
	s_mov_b64 s[8:9], 0x5062080
	v_add_u32_e32 v151, 0, v16
	v_mov_b64_e32 v[0:1], 0
	v_mov_b64_e32 v[2:3], 0
	v_mov_b64_e32 v[4:5], 0
	v_mov_b64_e32 v[6:7], 0
	v_mov_b64_e32 v[16:17], 0
	v_mov_b64_e32 v[18:19], 0
	v_mov_b64_e32 v[20:21], 0
	v_mov_b64_e32 v[22:23], 0
	s_waitcnt vmcnt(0)
	v_mov_b64_e32 v[32:33], 0
	v_mov_b64_e32 v[34:35], 0
	v_mov_b64_e32 v[36:37], 0
	v_mov_b64_e32 v[38:39], 0
	v_mov_b64_e32 v[48:49], 0
	v_mov_b64_e32 v[50:51], 0
	v_mov_b64_e32 v[52:53], 0
	v_mov_b64_e32 v[54:55], 0
	v_mov_b64_e32 v[8:9], 0
	v_mov_b64_e32 v[10:11], 0
	v_mov_b64_e32 v[12:13], 0
	v_mov_b64_e32 v[14:15], 0
	v_mov_b64_e32 v[24:25], 0
	v_mov_b64_e32 v[26:27], 0
	v_mov_b64_e32 v[28:29], 0
	v_mov_b64_e32 v[30:31], 0
	v_mov_b64_e32 v[40:41], 0
	v_mov_b64_e32 v[42:43], 0
	v_mov_b64_e32 v[44:45], 0
	v_mov_b64_e32 v[46:47], 0
	v_mov_b64_e32 v[56:57], 0
	v_mov_b64_e32 v[58:59], 0
	v_mov_b64_e32 v[60:61], 0
	v_mov_b64_e32 v[62:63], 0
	v_mov_b64_e32 v[64:65], 0
	v_mov_b64_e32 v[66:67], 0
	v_mov_b64_e32 v[68:69], 0
	v_mov_b64_e32 v[70:71], 0
	v_mov_b64_e32 v[80:81], 0
	v_mov_b64_e32 v[82:83], 0
	v_mov_b64_e32 v[84:85], 0
	v_mov_b64_e32 v[86:87], 0
	v_mov_b64_e32 v[96:97], 0
	v_mov_b64_e32 v[98:99], 0
	v_mov_b64_e32 v[100:101], 0
	v_mov_b64_e32 v[102:103], 0
	v_mov_b64_e32 v[112:113], 0
	v_mov_b64_e32 v[114:115], 0
	v_mov_b64_e32 v[116:117], 0
	v_mov_b64_e32 v[118:119], 0
	v_mov_b64_e32 v[72:73], 0
	v_mov_b64_e32 v[74:75], 0
	v_mov_b64_e32 v[76:77], 0
	v_mov_b64_e32 v[78:79], 0
	v_mov_b64_e32 v[88:89], 0
	v_mov_b64_e32 v[90:91], 0
	v_mov_b64_e32 v[92:93], 0
	v_mov_b64_e32 v[94:95], 0
	v_mov_b64_e32 v[104:105], 0
	v_mov_b64_e32 v[106:107], 0
	v_mov_b64_e32 v[108:109], 0
	v_mov_b64_e32 v[110:111], 0
	v_mov_b64_e32 v[120:121], 0
	v_mov_b64_e32 v[122:123], 0
	v_mov_b64_e32 v[124:125], 0
	v_mov_b64_e32 v[126:127], 0
	s_barrier

; template <class Epi, class Sched>
; __device__ __forceinline__ void gemm_phase(LAS unsigned char* lds, const int K, const Sched& S, const Epi& E) {
;     ...
;         for (int a = 0; a < 2; ++a)
; #pragma unroll
;             for (int b = 0; b < 2; ++b)
; #pragma unroll
;                 for (int m = 0; m < 4; ++m)
; #pragma unroll
;                     for (int n = 0; n < 2; ++n) acc[a][b][m][n] = (f32x4){0.f, 0.f, 0.f, 0.f};
.LBB0_532:
	s_mov_b32 s11, 0
	s_mov_b64 s[52:53], -1
	s_mov_b64 s[54:55], 0
	v_mov_b64_e32 v[0:1], 0
	v_mov_b64_e32 v[2:3], 0
	v_mov_b64_e32 v[4:5], 0
	v_mov_b64_e32 v[6:7], 0
	v_mov_b64_e32 v[12:13], 0
	v_mov_b64_e32 v[14:15], 0
	v_mov_b64_e32 v[20:21], 0
	v_mov_b64_e32 v[22:23], 0
	v_mov_b64_e32 v[28:29], 0
	v_mov_b64_e32 v[30:31], 0
	v_mov_b64_e32 v[36:37], 0
	v_mov_b64_e32 v[38:39], 0
	v_mov_b64_e32 v[44:45], 0
	v_mov_b64_e32 v[46:47], 0
	v_mov_b64_e32 v[52:53], 0
	v_mov_b64_e32 v[54:55], 0
	v_mov_b64_e32 v[8:9], 0
	v_mov_b64_e32 v[10:11], 0
	v_mov_b64_e32 v[16:17], 0
	v_mov_b64_e32 v[18:19], 0
	v_mov_b64_e32 v[24:25], 0
	v_mov_b64_e32 v[26:27], 0
	v_mov_b64_e32 v[32:33], 0
	v_mov_b64_e32 v[34:35], 0
	v_mov_b64_e32 v[40:41], 0
	v_mov_b64_e32 v[42:43], 0
	v_mov_b64_e32 v[48:49], 0
	v_mov_b64_e32 v[50:51], 0
	v_mov_b64_e32 v[56:57], 0
	v_mov_b64_e32 v[58:59], 0
	v_mov_b64_e32 v[60:61], 0
	v_mov_b64_e32 v[62:63], 0
	v_mov_b64_e32 v[64:65], 0
	v_mov_b64_e32 v[66:67], 0
	v_mov_b64_e32 v[68:69], 0
	v_mov_b64_e32 v[70:71], 0
	v_mov_b64_e32 v[76:77], 0
	v_mov_b64_e32 v[78:79], 0
	v_mov_b64_e32 v[84:85], 0
	v_mov_b64_e32 v[86:87], 0
	v_mov_b64_e32 v[92:93], 0
	v_mov_b64_e32 v[94:95], 0
	v_mov_b64_e32 v[100:101], 0
	v_mov_b64_e32 v[102:103], 0
	v_mov_b64_e32 v[108:109], 0
	v_mov_b64_e32 v[110:111], 0
	v_mov_b64_e32 v[116:117], 0
	v_mov_b64_e32 v[118:119], 0
	v_mov_b64_e32 v[72:73], 0
	v_mov_b64_e32 v[74:75], 0
	v_mov_b64_e32 v[80:81], 0
	v_mov_b64_e32 v[82:83], 0
	v_mov_b64_e32 v[88:89], 0
	v_mov_b64_e32 v[90:91], 0
	v_mov_b64_e32 v[96:97], 0
	v_mov_b64_e32 v[98:99], 0
	v_mov_b64_e32 v[104:105], 0
	v_mov_b64_e32 v[106:107], 0
	v_mov_b64_e32 v[112:113], 0
	v_mov_b64_e32 v[114:115], 0
	v_mov_b64_e32 v[120:121], 0
	v_mov_b64_e32 v[122:123], 0
	v_mov_b64_e32 v[124:125], 0
	v_mov_b64_e32 v[126:127], 0

; template <class Epi, class Sched>
; __device__ __forceinline__ void gemm_phase(LAS unsigned char* lds, const int K, const Sched& S, const Epi& E) {
;     ...
;         const char* nA = has_next ? nxt.a : cA; const char* nB = has_next ? nxt.b : cB;
;         const int nt = cur.pad;
; #pragma unroll 1
;         for (int t = 0; t < nt; t += 2) {
;             const bool last = (t == nt - 2);
;             const char* a1 = cA + (size_t)(t + 1) * kstep;
;             const char* a2 = last ? nA : cA + (size_t)(t + 2) * kstep; const char* b2 = last ? nB : cB + (size_t)(t + 2) * kstep;
;             const char* a3 = a2 + kstep; const char* b3 = b2 + kstep;
;     ...
;         for (int a = 0; a < 2; ++a)
; #pragma unroll
;             for (int b = 0; b < 2; ++b)
; #pragma unroll
;                 for (int m = 0; m < 4; ++m)
; #pragma unroll
;                     for (int n = 0; n < 2; ++n) acc[a][b][m][n] = (f32x4){0.f, 0.f, 0.f, 0.f};
.LBB0_811:
	s_and_b64 s[4:5], s[46:47], exec
	s_cselect_b32 s4, s43, s9
	s_cselect_b32 s5, s42, s8
	s_cselect_b32 s10, s45, s51
	s_cselect_b32 s11, s44, s50
	s_add_i32 s12, s2, -2
	s_add_u32 s13, s50, 0x100
	s_addc_u32 s14, s51, 0
	s_mov_b32 s15, 0
	v_mov_b64_e32 v[0:1], 0
	v_mov_b64_e32 v[2:3], 0
	v_mov_b64_e32 v[20:21], 0
	v_mov_b64_e32 v[22:23], 0
	v_mov_b64_e32 v[4:5], 0
	v_mov_b64_e32 v[6:7], 0
	v_mov_b64_e32 v[28:29], 0
	v_mov_b64_e32 v[30:31], 0
	v_mov_b64_e32 v[8:9], 0
	v_mov_b64_e32 v[10:11], 0
	s_waitcnt vmcnt(0)
	v_mov_b64_e32 v[36:37], 0
	v_mov_b64_e32 v[38:39], 0
	v_mov_b64_e32 v[12:13], 0
	v_mov_b64_e32 v[14:15], 0
	v_mov_b64_e32 v[44:45], 0
	v_mov_b64_e32 v[46:47], 0
	v_mov_b64_e32 v[60:61], 0
	v_mov_b64_e32 v[62:63], 0
	v_mov_b64_e32 v[96:97], 0
	v_mov_b64_e32 v[98:99], 0
	v_mov_b64_e32 v[68:69], 0
	v_mov_b64_e32 v[70:71], 0
	v_mov_b64_e32 v[100:101], 0
	v_mov_b64_e32 v[102:103], 0
	v_mov_b64_e32 v[72:73], 0
	v_mov_b64_e32 v[74:75], 0
	v_mov_b64_e32 v[104:105], 0
	v_mov_b64_e32 v[106:107], 0
	v_mov_b64_e32 v[76:77], 0
	v_mov_b64_e32 v[78:79], 0
	v_mov_b64_e32 v[108:109], 0
	v_mov_b64_e32 v[110:111], 0
	v_mov_b64_e32 v[16:17], 0
	v_mov_b64_e32 v[18:19], 0
	v_mov_b64_e32 v[48:49], 0
	v_mov_b64_e32 v[50:51], 0
	v_mov_b64_e32 v[24:25], 0
	v_mov_b64_e32 v[26:27], 0
	v_mov_b64_e32 v[52:53], 0
	v_mov_b64_e32 v[54:55], 0
	v_mov_b64_e32 v[32:33], 0
	v_mov_b64_e32 v[34:35], 0
	v_mov_b64_e32 v[56:57], 0
	v_mov_b64_e32 v[58:59], 0
	v_mov_b64_e32 v[40:41], 0
	v_mov_b64_e32 v[42:43], 0
	v_mov_b64_e32 v[64:65], 0
	v_mov_b64_e32 v[66:67], 0
	v_mov_b64_e32 v[80:81], 0
	v_mov_b64_e32 v[82:83], 0
	v_mov_b64_e32 v[112:113], 0
	v_mov_b64_e32 v[114:115], 0
	v_mov_b64_e32 v[84:85], 0
	v_mov_b64_e32 v[86:87], 0
	v_mov_b64_e32 v[116:117], 0
	v_mov_b64_e32 v[118:119], 0
	v_mov_b64_e32 v[88:89], 0
	v_mov_b64_e32 v[90:91], 0
	v_mov_b64_e32 v[120:121], 0
	v_mov_b64_e32 v[122:123], 0
	v_mov_b64_e32 v[92:93], 0
	v_mov_b64_e32 v[94:95], 0
	v_mov_b64_e32 v[124:125], 0
	v_mov_b64_e32 v[126:127], 0

; template <class Epi, class Sched>
; __device__ __forceinline__ void gemm_phase(LAS unsigned char* lds, const int K, const Sched& S, const Epi& E) {
;     ...
;             const char* a1 = cA + (size_t)(t + 1) * kstep;
;             const char* a2 = last ? nA : cA + (size_t)(t + 2) * kstep; const char* b2 = last ? nB : cB + (size_t)(t + 2) * kstep;
;             const char* a3 = a2 + kstep; const char* b3 = b2 + kstep;
;     ...
;         for (int a = 0; a < 2; ++a)
; #pragma unroll
;             for (int b = 0; b < 2; ++b)
; #pragma unroll
;                 for (int m = 0; m < 4; ++m)
; #pragma unroll
;                     for (int n = 0; n < 2; ++n) acc[a][b][m][n] = (f32x4){0.f, 0.f, 0.f, 0.f};
.LBB0_962:
	s_add_u32 s56, s56, 0x40080
	s_addc_u32 s57, s57, 0
	s_add_u32 s1, s58, 0x100
	s_addc_u32 s2, s59, 0
	s_mov_b32 s4, -2
	v_mov_b64_e32 v[0:1], 0
	v_mov_b64_e32 v[2:3], 0
	v_mov_b64_e32 v[8:9], 0
	v_mov_b64_e32 v[10:11], 0
	v_mov_b64_e32 v[16:17], 0
	v_mov_b64_e32 v[18:19], 0
	v_mov_b64_e32 v[24:25], 0
	v_mov_b64_e32 v[26:27], 0
	v_mov_b64_e32 v[32:33], 0
	v_mov_b64_e32 v[34:35], 0
	v_mov_b64_e32 v[40:41], 0
	v_mov_b64_e32 v[42:43], 0
	v_mov_b64_e32 v[48:49], 0
	v_mov_b64_e32 v[50:51], 0
	v_mov_b64_e32 v[56:57], 0
	v_mov_b64_e32 v[58:59], 0
	v_mov_b64_e32 v[4:5], 0
	v_mov_b64_e32 v[6:7], 0
	v_mov_b64_e32 v[12:13], 0
	v_mov_b64_e32 v[14:15], 0
	v_mov_b64_e32 v[20:21], 0
	v_mov_b64_e32 v[22:23], 0
	v_mov_b64_e32 v[28:29], 0
	v_mov_b64_e32 v[30:31], 0
	v_mov_b64_e32 v[36:37], 0
	v_mov_b64_e32 v[38:39], 0
	v_mov_b64_e32 v[44:45], 0
	v_mov_b64_e32 v[46:47], 0
	v_mov_b64_e32 v[52:53], 0
	v_mov_b64_e32 v[54:55], 0
	v_mov_b64_e32 v[60:61], 0
	v_mov_b64_e32 v[62:63], 0
	v_mov_b64_e32 v[64:65], 0
	v_mov_b64_e32 v[66:67], 0
	v_mov_b64_e32 v[72:73], 0
	v_mov_b64_e32 v[74:75], 0
	v_mov_b64_e32 v[80:81], 0
	v_mov_b64_e32 v[82:83], 0
	v_mov_b64_e32 v[88:89], 0
	v_mov_b64_e32 v[90:91], 0
	v_mov_b64_e32 v[96:97], 0
	v_mov_b64_e32 v[98:99], 0
	v_mov_b64_e32 v[104:105], 0
	v_mov_b64_e32 v[106:107], 0
	v_mov_b64_e32 v[112:113], 0
	v_mov_b64_e32 v[114:115], 0
	v_mov_b64_e32 v[120:121], 0
	v_mov_b64_e32 v[122:123], 0
	v_mov_b64_e32 v[68:69], 0
	v_mov_b64_e32 v[70:71], 0
	v_mov_b64_e32 v[76:77], 0
	v_mov_b64_e32 v[78:79], 0
	v_mov_b64_e32 v[84:85], 0
	v_mov_b64_e32 v[86:87], 0
	v_mov_b64_e32 v[92:93], 0
	v_mov_b64_e32 v[94:95], 0
	v_mov_b64_e32 v[100:101], 0
	v_mov_b64_e32 v[102:103], 0
	v_mov_b64_e32 v[108:109], 0
	v_mov_b64_e32 v[110:111], 0
	v_mov_b64_e32 v[116:117], 0
	v_mov_b64_e32 v[118:119], 0
	v_mov_b64_e32 v[124:125], 0
	v_mov_b64_e32 v[126:127], 0

; template <class Epi, class Sched>
; __device__ __forceinline__ void gemm_phase(LAS unsigned char* lds, const int K, const Sched& S, const Epi& E) {
;     ...
;         const char* nA = has_next ? nxt.a : cA; const char* nB = has_next ? nxt.b : cB;
;         const int nt = cur.pad;
; #pragma unroll 1
;         for (int t = 0; t < nt; t += 2) {
;             const bool last = (t == nt - 2);
;             const char* a1 = cA + (size_t)(t + 1) * kstep;
;             const char* a2 = last ? nA : cA + (size_t)(t + 2) * kstep; const char* b2 = last ? nB : cB + (size_t)(t + 2) * kstep;
;             const char* a3 = a2 + kstep; const char* b3 = b2 + kstep;
;     ...
;         for (int a = 0; a < 2; ++a)
; #pragma unroll
;             for (int b = 0; b < 2; ++b)
; #pragma unroll
;                 for (int m = 0; m < 4; ++m)
; #pragma unroll
;                     for (int n = 0; n < 2; ++n) acc[a][b][m][n] = (f32x4){0.f, 0.f, 0.f, 0.f};
.LBB0_1071:
	s_cmp_lt_i32 s51, 1
	s_cbranch_scc1 .LBB0_1087
	s_and_b64 s[0:1], s[48:49], exec
	s_cselect_b32 s0, s43, s9
	s_cselect_b32 s1, s42, s8
	s_cselect_b32 s2, s47, s53
	s_cselect_b32 s4, s46, s52
	s_add_i32 s5, s51, -2
	s_add_u32 s10, s52, 0x100
	s_addc_u32 s11, s53, 0
	s_mov_b32 s12, 0
	v_mov_b64_e32 v[0:1], 0
	v_mov_b64_e32 v[2:3], 0
	s_waitcnt vmcnt(0)
	v_mov_b64_e32 v[32:33], 0
	v_mov_b64_e32 v[34:35], 0
	v_mov_b64_e32 v[4:5], 0
	v_mov_b64_e32 v[6:7], 0
	v_mov_b64_e32 v[36:37], 0
	v_mov_b64_e32 v[38:39], 0
	v_mov_b64_e32 v[8:9], 0
	v_mov_b64_e32 v[10:11], 0
	v_mov_b64_e32 v[40:41], 0
	v_mov_b64_e32 v[42:43], 0
	v_mov_b64_e32 v[12:13], 0
	v_mov_b64_e32 v[14:15], 0
	v_mov_b64_e32 v[44:45], 0
	v_mov_b64_e32 v[46:47], 0
	v_mov_b64_e32 v[64:65], 0
	v_mov_b64_e32 v[66:67], 0
	v_mov_b64_e32 v[96:97], 0
	v_mov_b64_e32 v[98:99], 0
	v_mov_b64_e32 v[68:69], 0
	v_mov_b64_e32 v[70:71], 0
	v_mov_b64_e32 v[100:101], 0
	v_mov_b64_e32 v[102:103], 0
	v_mov_b64_e32 v[72:73], 0
	v_mov_b64_e32 v[74:75], 0
	v_mov_b64_e32 v[104:105], 0
	v_mov_b64_e32 v[106:107], 0
	v_mov_b64_e32 v[76:77], 0
	v_mov_b64_e32 v[78:79], 0
	v_mov_b64_e32 v[108:109], 0
	v_mov_b64_e32 v[110:111], 0
	v_mov_b64_e32 v[16:17], 0
	v_mov_b64_e32 v[18:19], 0
	v_mov_b64_e32 v[48:49], 0
	v_mov_b64_e32 v[50:51], 0
	v_mov_b64_e32 v[20:21], 0
	v_mov_b64_e32 v[22:23], 0
	v_mov_b64_e32 v[52:53], 0
	v_mov_b64_e32 v[54:55], 0
	v_mov_b64_e32 v[24:25], 0
	v_mov_b64_e32 v[26:27], 0
	v_mov_b64_e32 v[56:57], 0
	v_mov_b64_e32 v[58:59], 0
	v_mov_b64_e32 v[28:29], 0
	v_mov_b64_e32 v[30:31], 0
	v_mov_b64_e32 v[60:61], 0
	v_mov_b64_e32 v[62:63], 0
	v_mov_b64_e32 v[80:81], 0
	v_mov_b64_e32 v[82:83], 0
	v_mov_b64_e32 v[112:113], 0
	v_mov_b64_e32 v[114:115], 0
	v_mov_b64_e32 v[84:85], 0
	v_mov_b64_e32 v[86:87], 0
	v_mov_b64_e32 v[116:117], 0
	v_mov_b64_e32 v[118:119], 0
	v_mov_b64_e32 v[88:89], 0
	v_mov_b64_e32 v[90:91], 0
	v_mov_b64_e32 v[120:121], 0
	v_mov_b64_e32 v[122:123], 0
	v_mov_b64_e32 v[92:93], 0
	v_mov_b64_e32 v[94:95], 0
	v_mov_b64_e32 v[124:125], 0
	v_mov_b64_e32 v[126:127], 0
